# out-proj unit: first weight (B operand) K-tile halves fetched by LDS-DMA before the P4-P5 panel barrier instead of after it
# baseline (speedup 1.0000x reference)
.LBB0_566:
	s_cmp_gt_i32 s27, 5
	s_cselect_b64 s[4:5], -1, 0
	s_and_b64 s[6:7], s[6:7], s[4:5]
	s_andn2_b64 vcc, exec, s[6:7]
	s_cbranch_vccnz .LBB0_616
	s_waitcnt vmcnt(0)
	v_cmp_eq_u32_e32 vcc, 0, v0
	s_waitcnt vmcnt(0) lgkmcnt(0)
	s_barrier
	v_lshlrev_b32_e32 v20, 4, v0
	v_and_b32_e32 v21, 32, v0
	v_lshrrev_b32_e32 v22, 1, v0
	v_and_b32_e32 v22, 24, v22
	v_lshrrev_b32_e32 v23, 5, v0
	v_and_b32_e32 v23, 4, v23
	v_bfe_u32 v24, v0, 2, 2
	v_bitop3_b32 v25, v20, v21, 48 bitop3:0x6c
	v_and_b32_e32 v26, 64, v0
	v_or3_b32 v22, v23, v24, v22
	v_lshrrev_b32_e32 v23, 3, v0
	v_or_b32_e32 v27, 0x2000, v20
	v_or_b32_e32 v21, v25, v26
	v_and_or_b32 v23, v23, 32, v22
	v_lshrrev_b32_e32 v20, 7, v27
	v_lshl_or_b32 v28, v23, 12, v21
	s_movk_i32 s50, 0x60
	v_and_or_b32 v20, v20, s50, v22
	v_lshl_or_b32 v29, v20, 12, v21
	v_readfirstlane_b32 s51, v0
	s_lshr_b32 s51, s51, 6
	s_lshl_b32 s51, s51, 10
	s_lshr_b32 s52, s2, 5
	s_lshl_b32 s52, s52, 20
	s_add_u32 s54, s24, 0x1e00000
	s_addc_u32 s55, s25, 0
	s_add_u32 s54, s54, s52
	s_addc_u32 s55, s55, 0
	s_add_u32 s56, s54, 0x80000
	s_addc_u32 s57, s55, 0
	s_add_i32 m0, s51, 0x10000
	s_nop 0
	global_load_lds_dwordx4 v28, s[54:55]
	s_add_i32 m0, s51, 0x12000
	s_nop 0
	global_load_lds_dwordx4 v29, s[54:55]
	s_add_i32 m0, s51, 0x14000
	s_nop 0
	global_load_lds_dwordx4 v28, s[56:57]
	s_add_i32 m0, s51, 0x16000
	s_nop 0
	global_load_lds_dwordx4 v29, s[56:57]
	s_and_saveexec_b64 s[6:7], vcc
	s_cbranch_execz .LBB0_615
	s_and_b32 s8, s2, 7
	s_lshl_b32 s8, s8, 2
	s_bfe_u32 s9, s2, 0x20003
	s_add_i32 s8, s8, s9
	s_lshl_b32 s8, s8, 6
	s_add_i32 s8, s8, 0x6400
	v_mov_b32_e32 v1, s8
	s_mul_i32 s9, s33, s33
	s_lshl_b32 s9, s9, 16
	s_lshl_b32 s10, s33, 8
	s_or_b32 s9, s9, s10
	s_or_b32 s9, s9, 1
	v_mov_b32_e32 v2, s9
	global_atomic_add v1, v2, s[24:25]
	s_mov_b64 s[70:71], exec
	s_mov_b64 exec, -1
	s_load_dwordx2 s[90:91], s[0:1], 0x0
	s_and_b32 s80, s2, 7
	s_lshl_b32 s80, s80, 2
	s_bfe_u32 s81, s2, 0x20003
	s_add_i32 s80, s80, s81
	s_lshr_b32 s81, s2, 5
	s_lshl_b32 s80, s80, 21
	s_lshl_b32 s81, s81, 10
	s_add_u32 s80, s80, s81
	s_lshr_b32 s82, s28, 2
	s_lshl_b32 s82, s82, 19
	s_add_u32 s80, s80, s82
	s_and_b32 s82, s28, 3
	s_lshl_b32 s82, s82, 7
	s_add_u32 s80, s80, s82
	v_and_b32_e32 v202, 15, v0
	v_lshlrev_b32_e32 v202, 13, v202
	v_bfe_u32 v203, v0, 4, 2
	v_lshl_or_b32 v202, v203, 5, v202
	s_waitcnt lgkmcnt(0)
	s_add_u32 s90, s90, s80
	s_addc_u32 s91, s91, 0
	global_load_dwordx4 v[126:129], v202, s[90:91] nt
	global_load_dwordx4 v[122:125], v202, s[90:91] offset:16 nt
	global_load_dwordx4 v[118:121], v202, s[90:91] offset:512 nt
	global_load_dwordx4 v[114:117], v202, s[90:91] offset:528 nt
	s_add_u32 s90, s90, 0x20000
	s_addc_u32 s91, s91, 0
	global_load_dwordx4 v[110:113], v202, s[90:91] nt
	global_load_dwordx4 v[106:109], v202, s[90:91] offset:16 nt
	global_load_dwordx4 v[102:105], v202, s[90:91] offset:512 nt
	global_load_dwordx4 v[98:101], v202, s[90:91] offset:528 nt
	s_add_u32 s90, s90, 0x20000
	s_addc_u32 s91, s91, 0
	global_load_dwordx4 v[94:97], v202, s[90:91] nt
	global_load_dwordx4 v[90:93], v202, s[90:91] offset:16 nt
	global_load_dwordx4 v[86:89], v202, s[90:91] offset:512 nt
	global_load_dwordx4 v[154:157], v202, s[90:91] offset:528 nt
	s_add_u32 s90, s90, 0x20000
	s_addc_u32 s91, s91, 0
	global_load_dwordx4 v[82:85], v202, s[90:91] nt
	global_load_dwordx4 v[158:161], v202, s[90:91] offset:16 nt
	global_load_dwordx4 v[162:165], v202, s[90:91] offset:512 nt
	global_load_dwordx4 v[166:169], v202, s[90:91] offset:528 nt
	s_add_u32 s90, s90, 0xa0000
	s_addc_u32 s91, s91, 0
	global_load_dwordx4 v[170:173], v202, s[90:91] nt
	global_load_dwordx4 v[174:177], v202, s[90:91] offset:16 nt
	global_load_dwordx4 v[178:181], v202, s[90:91] offset:512 nt
	global_load_dwordx4 v[182:185], v202, s[90:91] offset:528 nt
	s_add_u32 s90, s90, 0x20000
	s_addc_u32 s91, s91, 0
	global_load_dwordx4 v[186:189], v202, s[90:91] nt
	global_load_dwordx4 v[190:193], v202, s[90:91] offset:16 nt
	global_load_dwordx4 v[194:197], v202, s[90:91] offset:512 nt
	global_load_dwordx4 v[198:201], v202, s[90:91] offset:528 nt
	s_add_u32 s90, s90, 0x20000
	s_addc_u32 s91, s91, 0
	global_load_dwordx4 v[206:209], v202, s[90:91] nt
	global_load_dwordx4 v[210:213], v202, s[90:91] offset:16 nt
	global_load_dwordx4 v[214:217], v202, s[90:91] offset:512 nt
	global_load_dwordx4 v[218:221], v202, s[90:91] offset:528 nt
	s_add_u32 s90, s90, 0x20000
	s_addc_u32 s91, s91, 0
	global_load_dwordx4 v[222:225], v202, s[90:91] nt
	global_load_dwordx4 v[226:229], v202, s[90:91] offset:16 nt
	global_load_dwordx4 v[230:233], v202, s[90:91] offset:512 nt
	global_load_dwordx4 v[234:237], v202, s[90:91] offset:528 nt

.LBB0_616:
	s_cmp_lt_i32 s26, 6
	s_cselect_b64 s[6:7], -1, 0
	s_and_b64 s[4:5], s[6:7], s[4:5]
	s_andn2_b64 vcc, exec, s[4:5]
	s_cbranch_vccnz .LBB0_664
	s_cmpk_gt_i32 s2, 0xff
	v_readfirstlane_b32 s33, v0
	s_cbranch_scc1 .LBB0_664
	s_and_b32 s80, s2, 7
	s_lshl_b32 s80, s80, 2
	s_bfe_u32 s81, s2, 0x20003
	s_add_i32 s80, s80, s81
	s_lshr_b32 s80, s80, 4
	s_mul_i32 s80, s80, 0x6000
	s_lshr_b32 s81, s2, 5
	s_lshl_b32 s81, s81, 10
	s_add_u32 s80, s80, s81
	s_lshr_b32 s81, s33, 6
	s_and_b32 s81, s81, 3
	s_lshl_b32 s81, s81, 7
	s_add_u32 s80, s80, s81
	s_add_u32 s80, s80, 0x2904000
	s_add_u32 s92, s24, s80
	s_addc_u32 s93, s25, 0
	v_bfe_u32 v205, v0, 4, 2
	v_lshlrev_b32_e32 v205, 5, v205
	global_load_dwordx4 v[146:149], v205, s[92:93] sc1
	global_load_dwordx4 v[242:245], v205, s[92:93] offset:16 sc1
	global_load_dwordx4 v[246:249], v205, s[92:93] offset:512 sc1
	global_load_dwordx4 v[250:253], v205, s[92:93] offset:528 sc1
	v_lshrrev_b32_e32 v150, 1, v0
	s_waitcnt lgkmcnt(0)
	v_lshrrev_b32_e32 v4, 5, v0
	v_lshlrev_b32_e32 v1, 4, v0
	v_and_b32_e32 v2, 32, v0
	v_and_b32_e32 v3, 24, v150
	v_and_b32_e32 v4, 4, v4
	v_bfe_u32 v5, v0, 2, 2
	s_add_u32 s37, s24, 0xe000000
	v_bfe_u32 v12, v0, 2, 4
	v_bitop3_b32 v10, v1, v2, 48 bitop3:0x6c
	v_and_b32_e32 v11, 64, v0
	v_or3_b32 v3, v4, v5, v3
	v_lshrrev_b32_e32 v4, 3, v0
	v_or_b32_e32 v13, 0x2000, v1
	s_addc_u32 s38, s25, 0
	v_or_b32_e32 v2, v10, v11
	v_and_or_b32 v5, v4, 48, v12
	v_and_or_b32 v4, v4, 32, v3
	v_lshrrev_b32_e32 v1, 7, v13
	s_movk_i32 s4, 0x70
	s_add_u32 s39, s24, 0x1e00000
	v_lshl_or_b32 v132, v4, 12, v2
	v_and_or_b32 v4, v1, s4, v12
	s_movk_i32 s4, 0x60
	s_addc_u32 s40, s25, 0
	s_ashr_i32 s42, s2, 31
	v_and_or_b32 v1, v1, s4, v3
	s_lshr_b32 s4, s42, 29
	s_add_i32 s4, s2, s4
	s_ashr_i32 s5, s4, 3
	s_and_b32 s4, s4, -8
	s_lshr_b32 s11, s33, 6
	s_sub_i32 s4, s2, s4
	s_lshr_b32 s36, s33, 8
	s_lshl_b32 s41, s11, 10
	s_lshl_b32 s7, s4, 5
	s_mul_i32 s6, s4, 33
	s_cmp_lt_i32 s4, 0
	s_cselect_b32 s4, s6, s7
	s_add_i32 s4, s4, s5
	s_ashr_i32 s5, s4, 31
	s_lshr_b32 s5, s5, 27
	s_add_i32 s5, s4, s5
	s_ashr_i32 s6, s5, 5
	s_and_b32 s5, s5, 0xffe0
	s_sub_i32 s5, s4, s5
	s_bfe_i32 s4, s5, 0x80000
	s_bfe_u32 s4, s4, 0x2000d
	s_add_i32 s7, s5, s4
	s_bfe_i32 s4, s7, 0x80000
	s_and_b32 s7, s7, 0xfc
	s_sub_i32 s5, s5, s7
	s_lshl_b32 s6, s6, 2
	s_sext_i32_i16 s4, s4
	s_sext_i32_i8 s5, s5
	s_lshr_b32 s4, s4, 2
	s_add_i32 s8, s6, s5
	s_ashr_i32 s9, s8, 31
	s_bfe_i64 s[12:13], s[4:5], 0x100000
	s_lshl_b64 s[6:7], s[8:9], 20
	s_lshl_b64 s[12:13], s[12:13], 20
	s_add_u32 s28, s39, s12
	s_addc_u32 s29, s40, s13
	s_add_i32 s43, s41, 0
	s_add_i32 m0, s43, 0x10000
	v_lshl_or_b32 v136, v1, 12, v2
	s_add_i32 m0, s43, 0x12000
	s_add_u32 s12, s28, 0x80000
	s_addc_u32 s13, s29, 0
	s_add_i32 m0, s43, 0x14000
	v_lshl_or_b32 v130, v5, 12, v2
	s_add_i32 m0, s43, 0x16000
	v_lshl_or_b32 v134, v4, 12, v2
	s_add_u32 s12, s37, s6
	s_addc_u32 s13, s38, s7
	s_add_i32 s44, s43, 0x2000
	s_mov_b32 m0, s43
	s_add_u32 s6, s12, 0x80000
	global_load_lds_dwordx4 v130, s[12:13]
	s_mov_b32 m0, s44
	s_addc_u32 s7, s13, 0
	s_add_i32 s45, s43, 0x4000
	global_load_lds_dwordx4 v134, s[12:13]
	s_mov_b32 m0, s45
	s_add_i32 s46, s43, 0x6000
	global_load_lds_dwordx4 v130, s[6:7]
	s_mov_b32 m0, s46
	v_mov_b32_e32 v133, 0
	global_load_lds_dwordx4 v134, s[6:7]
	v_mov_b32_e32 v137, v133
	v_mov_b32_e32 v131, v133
	v_mov_b32_e32 v135, v133
	v_lshl_add_u64 v[8:9], s[28:29], 0, v[132:133]
	v_lshl_add_u64 v[6:7], s[28:29], 0, v[136:137]
	v_lshl_add_u64 v[4:5], s[12:13], 0, v[130:131]
	s_cmp_lg_u32 s36, 1
	v_lshl_add_u64 v[2:3], s[12:13], 0, v[134:135]
	s_cbranch_scc1 .LBB0_620
	s_barrier
